# grid barrier leader: per-XCD release and own invalidate issued back to back right after the top-level arrival, one wait instead of two
# speedup vs baseline: 1.0064x; 1.0064x over previous
.LBB0_170:
	s_or_b64 exec, exec, s[6:7]
	v_mov_b32_e32 v0, 1
	v_mov_b32_e32 v2, 0x2000
	global_atomic_add v2, v0, s[4:5] offset:1024
	buffer_inv sc1
	s_waitcnt vmcnt(0)

.LBB0_334:
	s_or_b64 exec, exec, s[4:5]
	v_mov_b32_e32 v0, 1
	v_mov_b32_e32 v2, 0x2000
	global_atomic_add v2, v0, s[6:7] offset:1024
	buffer_inv sc1
	s_waitcnt vmcnt(0)

.LBB0_1554:
	s_or_b64 exec, exec, s[4:5]
	v_mov_b32_e32 v0, 1
	v_mov_b32_e32 v2, 0x2000
	global_atomic_add v2, v0, s[8:9] offset:1024
	buffer_inv sc1
	s_waitcnt vmcnt(0)
